# attention: wave-aligned key-row streaming with context steps reordered (no extra steps), per-round workgroup barrier; other changes as before
# speedup vs baseline: 1.0077x; 1.0077x over previous
; __device__ __forceinline__ void attn_phase(const Args& a, int layer, LAS unsigned char* lds, int G, int need_ctx) {
;     ...
;         const int r0a = min(max(r - 4, 0), 24), r0b = min(max(r - 3, 0), 24), nband = lat ? (r0b + 8 - r0a) : 0;
;         const int qr = r + (q >> 4), myr0 = (q >> 4) ? r0b : r0a;
;         const int cw = min(max(16 * j - 8, 0), 32), qcol = 16 * j + (q & 15), c0 = min(max(qcol - 8, 0), 48);
;         const int nst = nband + 8;
;         const int kb_lat = b * SEQ + r0a * 64 + cw, kb_ctx = MLAT + b * CTX;
;         const bf16_t* kbase = Kp + (size_t)h * 1024 + (size_t)(sig >> 3) * 32768 + (sig & 7) * 16 + 8 * hh;
;         const bf16_t* vbase = Vt + (size_t)h * 1024 + (size_t)hh * 32768 + q * 8;
;         float m_run = -1e30f, l_run = 0.f;
;         f32x16 OT[4];
; #pragma unroll
;         for (int d = 0; d < 4; ++d)
; #pragma unroll
;             for (int t = 0; t < 16; ++t) OT[d][t] = 0.f;
.LBB0_152:
	v_sub_u32_e64 v0, s6, 4 clamp
	v_mov_b32_e32 v15, 0
	v_readfirstlane_b32 s4, v0
	v_sub_u32_e64 v0, s6, 3 clamp
	s_min_u32 s37, s4, 24
	v_readfirstlane_b32 s4, v0
	s_min_u32 s4, s4, 24
	s_sub_i32 s5, s4, s37
	s_add_i32 s5, s5, 8
	s_andn2_b32 s100, s6, 2
	s_sub_i32 s100, s100, 4
	s_max_i32 s100, s100, 0
	s_min_i32 s100, s100, 24
	s_mov_b32 vcc_lo, s37
	s_mov_b32 s37, s100
	s_sub_i32 s100, vcc_lo, s100
	s_and_b64 s[0:1], s[0:1], exec
	s_cselect_b32 s15, s5, 0
	s_cmp_lt_i32 s15, -7
	v_mov_b32_e32 v14, v15
	v_mov_b32_e32 v13, v15
	v_mov_b32_e32 v12, v15
	v_mov_b32_e32 v11, v15
	v_mov_b32_e32 v10, v15
	v_mov_b32_e32 v9, v15
	v_mov_b32_e32 v8, v15
	v_mov_b32_e32 v7, v15
	v_mov_b32_e32 v6, v15
	v_mov_b32_e32 v5, v15
	v_mov_b32_e32 v4, v15
	v_mov_b32_e32 v3, v15
	v_mov_b32_e32 v2, v15
	v_mov_b32_e32 v1, v15
	v_mov_b32_e32 v0, v15
	v_mov_b32_e32 v31, v15
	v_mov_b32_e32 v30, v15
	v_mov_b32_e32 v29, v15
	v_mov_b32_e32 v28, v15
	v_mov_b32_e32 v27, v15
	v_mov_b32_e32 v26, v15
	v_mov_b32_e32 v25, v15
	v_mov_b32_e32 v24, v15
	v_mov_b32_e32 v23, v15
	v_mov_b32_e32 v22, v15
	v_mov_b32_e32 v21, v15
	v_mov_b32_e32 v20, v15
	v_mov_b32_e32 v19, v15
	v_mov_b32_e32 v18, v15
	v_mov_b32_e32 v17, v15
	v_mov_b32_e32 v16, v15
	v_mov_b32_e32 v47, v15
	v_mov_b32_e32 v46, v15
	v_mov_b32_e32 v45, v15
	v_mov_b32_e32 v44, v15
	v_mov_b32_e32 v43, v15
	v_mov_b32_e32 v42, v15
	v_mov_b32_e32 v41, v15
	v_mov_b32_e32 v40, v15
	v_mov_b32_e32 v39, v15
	v_mov_b32_e32 v38, v15
	v_mov_b32_e32 v37, v15
	v_mov_b32_e32 v36, v15
	v_mov_b32_e32 v35, v15
	v_mov_b32_e32 v34, v15
	v_mov_b32_e32 v33, v15
	v_mov_b32_e32 v32, v15
	v_mov_b32_e32 v63, v15
	v_mov_b32_e32 v62, v15
	v_mov_b32_e32 v61, v15
	v_mov_b32_e32 v60, v15
	v_mov_b32_e32 v59, v15
	v_mov_b32_e32 v58, v15
	v_mov_b32_e32 v57, v15
	v_mov_b32_e32 v56, v15
	v_mov_b32_e32 v55, v15
	v_mov_b32_e32 v54, v15
	v_mov_b32_e32 v53, v15
	v_mov_b32_e32 v52, v15
	v_mov_b32_e32 v51, v15
	v_mov_b32_e32 v50, v15
	v_mov_b32_e32 v49, v15
	v_mov_b32_e32 v48, v15
	v_mov_b32_e32 v64, v15
	s_cbranch_scc1 .LBB0_199
; __device__ __forceinline__ void attn_phase(const Args& a, int layer, LAS unsigned char* lds, int G, int need_ctx) {
;     ...
;         const int cw = min(max(16 * j - 8, 0), 32), qcol = 16 * j + (q & 15), c0 = min(max(qcol - 8, 0), 48);
;         const int nst = nband + 8;
;         const int kb_lat = b * SEQ + r0a * 64 + cw, kb_ctx = MLAT + b * CTX;
;         const bf16_t* kbase = Kp + (size_t)h * 1024 + (size_t)(sig >> 3) * 32768 + (sig & 7) * 16 + 8 * hh;
;         const bf16_t* vbase = Vt + (size_t)h * 1024 + (size_t)hh * 32768 + q * 8;
;         float m_run = -1e30f, l_run = 0.f;
;         f32x16 OT[4];
; #pragma unroll
;         for (int d = 0; d < 4; ++d)
; #pragma unroll
;             for (int t = 0; t < 16; ++t) OT[d][t] = 0.f;
;         bf16x8 kreg[8], vreg[8];
;         { const int kb0 = nband ? kb_lat : kb_ctx;
; #pragma unroll
;           for (int c = 0; c < 8; ++c) kreg[c] = *(const bf16x8*)(kbase + (size_t)(kb0 >> 3) * 32768 + 128 * c); }
;         for (int st = 0; st < nst; ++st) {
;             const bool isl = st < nband;
;             const int keybase = isl ? kb_lat + st * 64 : kb_ctx + 32 * (st - nband);
; #pragma unroll
;             for (int d = 0; d < 4; ++d)
; #pragma unroll
;                 for (int s2 = 0; s2 < 2; ++s2) vreg[d * 2 + s2] = *(const bf16x8*)(vbase + (size_t)(keybase >> 3) * 32768 + s2 * 65536 + d * 256);
;             f32x16 sc;
; #pragma unroll
;             for (int t = 0; t < 16; ++t) sc[t] = 0.f;
; #pragma unroll
;             for (int c = 0; c < 8; ++c) sc = __builtin_amdgcn_mfma_f32_32x32x16_bf16(kreg[c], qf[c], sc, 0, 0, 0);
;             if (st + 1 < nst) {
;                 const int kn = (st + 1 < nband) ? kb_lat + (st + 1) * 64 : kb_ctx + 32 * (st + 1 - nband);
; #pragma unroll
;                 for (int c = 0; c < 8; ++c) kreg[c] = *(const bf16x8*)(kbase + (size_t)(kn >> 3) * 32768 + 128 * c);
	v_sub_u32_e64 v0, s7, 8 clamp
	s_lshl_b32 s0, s23, 11
	s_lshl_b32 s1, s37, 6
	v_readfirstlane_b32 s5, v0
	s_or_b32 s0, s1, s0
	s_lshl_b32 s1, s23, 8
	s_min_u32 s12, s5, 32
	s_or_b32 s24, s0, s12
	s_add_i32 s13, s1, 0x2000
	v_readlane_b32 s0, v250, 8
	v_mov_b32_e32 v0, s4
	s_add_i32 s1, s37, s100
	v_mov_b32_e32 v2, s1
	v_readlane_b32 s1, v250, 9
	s_lshl_b32 s94, s36, 11
	s_add_i32 s25, s15, 8
	v_cndmask_b32_e64 v96, v0, v2, s[0:1]
	s_mov_b32 s1, s95
	v_writelane_b32 v250, s0, 12
	s_cmp_eq_u32 s15, 0
	v_or_b32_e32 v1, s7, v230
	v_writelane_b32 v250, s1, 13
	s_cselect_b32 s0, s13, s24
	s_cmp_lg_u32 s100, 0
	s_cselect_b32 s0, s13, s0
	s_ashr_i32 s0, s0, 3
	v_max_i32_e32 v0, 8, v1
	s_ashr_i32 s1, s0, 31
	v_lshl_add_u64 v[206:207], v[198:199], 0, s[94:95]
	v_add_u32_e32 v0, -8, v0
	s_lshl_b64 s[0:1], s[0:1], 16
	v_min_u32_e32 v2, 48, v0
	v_lshl_add_u64 v[0:1], v[206:207], 0, s[0:1]
	global_load_dwordx4 v[130:133], v[0:1], off offset:1792
	global_load_dwordx4 v[134:137], v[0:1], off offset:1536
	global_load_dwordx4 v[138:141], v[0:1], off offset:1280
	global_load_dwordx4 v[142:145], v[0:1], off offset:1024
	global_load_dwordx4 v[158:161], v[0:1], off offset:768
	global_load_dwordx4 v[154:157], v[0:1], off offset:512
	global_load_dwordx4 v[150:153], v[0:1], off offset:256
	global_load_dwordx4 v[146:149], v[0:1], off
	v_xor_b32_e32 v3, 32, v210
	v_cmp_lt_i32_e32 vcc, v3, v212
	v_add_u32_e32 v0, s12, v196
	v_add_u32_e32 v1, 16, v2
	v_cndmask_b32_e32 v3, v210, v3, vcc
	v_lshlrev_b32_e32 v235, 2, v3
	v_or_b32_e32 v3, 1, v0
	v_cmp_ge_u32_e64 s[40:41], v3, v2
	v_cmp_lt_u32_e64 s[42:43], v3, v1
	v_or_b32_e32 v3, 2, v0
	v_cmp_ge_u32_e64 s[44:45], v3, v2
	v_cmp_lt_u32_e64 s[46:47], v3, v1
	v_or_b32_e32 v3, 3, v0
	v_cmp_ge_u32_e64 s[48:49], v3, v2
	v_cmp_lt_u32_e64 s[50:51], v3, v1
	v_or_b32_e32 v3, 4, v0
	v_cmp_ge_u32_e64 s[52:53], v3, v2
	v_cmp_lt_u32_e64 s[54:55], v3, v1
	v_or_b32_e32 v3, 5, v0
	v_cmp_ge_u32_e64 s[56:57], v3, v2
	v_cmp_lt_u32_e64 s[58:59], v3, v1
	v_or_b32_e32 v3, 6, v0
	v_cmp_ge_u32_e64 s[60:61], v3, v2
	v_cmp_lt_u32_e64 s[62:63], v3, v1
	v_or_b32_e32 v3, 7, v0
	v_cmp_ge_u32_e64 s[64:65], v3, v2
	v_cmp_lt_u32_e64 s[66:67], v3, v1
	v_add_u32_e32 v3, 16, v0
	v_cmp_ge_u32_e64 s[68:69], v3, v2
	v_add_u32_e32 v3, 17, v0
	v_cmp_ge_u32_e64 s[72:73], v3, v2
	v_cmp_lt_u32_e64 s[74:75], v3, v1
	v_add_u32_e32 v3, 18, v0
	v_cmp_ge_u32_e64 s[76:77], v3, v2
	v_cmp_lt_u32_e64 s[78:79], v3, v1
	v_add_u32_e32 v3, 19, v0
	v_cmp_ge_u32_e64 s[82:83], v3, v2
	v_cmp_lt_u32_e64 s[84:85], v3, v1
	v_add_u32_e32 v3, 20, v0
	v_cmp_ge_u32_e64 s[86:87], v3, v2
	v_cmp_lt_u32_e64 s[88:89], v3, v1
	v_add_u32_e32 v3, 21, v0
	v_cmp_ge_u32_e64 s[0:1], v0, v2
	v_cmp_lt_u32_e64 s[38:39], v0, v1
	v_cmp_lt_u32_e64 s[70:71], v0, v2
	v_cmp_ge_u32_e64 s[90:91], v3, v2
	v_cmp_lt_u32_e64 s[92:93], v3, v1
	v_add_u32_e32 v3, 22, v0
	v_add_u32_e32 v0, 23, v0
	v_cmp_lt_u32_e64 s[96:97], v3, v1
	v_cmp_ge_u32_e64 s[98:99], v0, v2
	v_cmp_lt_u32_e64 s[4:5], v0, v1
	s_mul_i32 s23, s37, 31
	v_add_u32_e32 v0, s7, v230
	v_add_u32_e32 v1, s6, v229
	v_sub_u32_e32 v0, s23, v0
	v_mul_u32_u24_e32 v1, 31, v1
	v_sub_u32_e32 v0, v0, v1
	s_lshl_b32 s12, s12, 2
	v_lshlrev_b32_e32 v0, 2, v0
	s_lshl_b32 s6, s15, 5
	v_mov_b32_e32 v237, 0
	v_lshl_add_u64 v[208:209], v[200:201], 0, s[94:95]
	s_mov_b32 s27, 0
	v_add_u32_e32 v234, 8, v96
	v_cmp_ge_u32_e64 s[94:95], v3, v2
	v_add3_u32 v236, s12, v0, v233
	s_sub_i32 s23, s13, s6
	v_mov_b32_e32 v254, 0xff61b1e6
	v_mov_b32_e32 v238, 0xf149f2ca
	v_mov_b32_e32 v48, 0
	v_mov_b32_e32 v49, v237
	v_mov_b32_e32 v50, v237
	v_mov_b32_e32 v51, v237
	v_mov_b32_e32 v52, v237
	v_mov_b32_e32 v53, v237
	v_mov_b32_e32 v54, v237
	v_mov_b32_e32 v55, v237
	v_mov_b32_e32 v56, v237
	v_mov_b32_e32 v57, v237
	v_mov_b32_e32 v58, v237
	v_mov_b32_e32 v59, v237
	v_mov_b32_e32 v60, v237
	v_mov_b32_e32 v61, v237
	v_mov_b32_e32 v62, v237
	v_mov_b32_e32 v63, v237
	v_mov_b32_e32 v32, 0
	v_mov_b32_e32 v33, v237
	v_mov_b32_e32 v34, v237
	v_mov_b32_e32 v35, v237
	v_mov_b32_e32 v36, v237
	v_mov_b32_e32 v37, v237
	v_mov_b32_e32 v38, v237
	v_mov_b32_e32 v39, v237
	v_mov_b32_e32 v40, v237
	v_mov_b32_e32 v41, v237
	v_mov_b32_e32 v42, v237
	v_mov_b32_e32 v43, v237
	v_mov_b32_e32 v44, v237
	v_mov_b32_e32 v45, v237
	v_mov_b32_e32 v46, v237
	v_mov_b32_e32 v47, v237
	v_mov_b32_e32 v16, 0
	v_mov_b32_e32 v17, v237
	v_mov_b32_e32 v18, v237
	v_mov_b32_e32 v19, v237
	v_mov_b32_e32 v20, v237
	v_mov_b32_e32 v21, v237
	v_mov_b32_e32 v22, v237
	v_mov_b32_e32 v23, v237
	v_mov_b32_e32 v24, v237
	v_mov_b32_e32 v25, v237
	v_mov_b32_e32 v26, v237
	v_mov_b32_e32 v27, v237
	v_mov_b32_e32 v28, v237
	v_mov_b32_e32 v29, v237
	v_mov_b32_e32 v30, v237
	v_mov_b32_e32 v31, v237
	v_mov_b32_e32 v0, 0
	v_mov_b32_e32 v1, v237
	v_mov_b32_e32 v2, v237
	v_mov_b32_e32 v3, v237
	v_mov_b32_e32 v4, v237
	v_mov_b32_e32 v5, v237
	v_mov_b32_e32 v6, v237
	v_mov_b32_e32 v7, v237
	v_mov_b32_e32 v8, v237
	v_mov_b32_e32 v9, v237
	v_mov_b32_e32 v10, v237
	v_mov_b32_e32 v11, v237
	v_mov_b32_e32 v12, v237
	v_mov_b32_e32 v13, v237
	v_mov_b32_e32 v14, v237
	v_mov_b32_e32 v15, v237
	s_barrier
.LBB0_154:
	s_sub_i32 s12, s27, s100
	s_cmp_lt_u32 s12, s15
	s_cselect_b64 s[6:7], -1, 0
	s_cbranch_scc1 .Latt_lat_cur
	s_mov_b32 s12, s23
	s_cmp_lt_i32 s27, s100
	s_cbranch_scc0 .LBB0_156
	s_lshl_b32 s13, s15, 5
	s_add_i32 s12, s12, s13
	s_branch .LBB0_156
.Latt_lat_cur:
	s_lshl_b32 s12, s27, 6
	s_add_i32 s12, s12, s24
.LBB0_156:
	s_ashr_i32 s12, s12, 3
	s_ashr_i32 s13, s12, 31
	s_lshl_b64 s[12:13], s[12:13], 16
	v_lshl_add_u64 v[64:65], v[208:209], 0, s[12:13]
	v_add_co_u32_e32 v66, vcc, 0x20000, v64
	global_load_dwordx4 v[190:193], v[64:65], off
	s_nop 0
	v_addc_co_u32_e32 v67, vcc, 0, v65, vcc
	global_load_dwordx4 v[186:189], v[66:67], off
	global_load_dwordx4 v[182:185], v[64:65], off offset:512
	global_load_dwordx4 v[178:181], v[66:67], off offset:512
	global_load_dwordx4 v[174:177], v[64:65], off offset:1024
	global_load_dwordx4 v[170:173], v[66:67], off offset:1024
	global_load_dwordx4 v[166:169], v[64:65], off offset:1536
	global_load_dwordx4 v[162:165], v[66:67], off offset:1536
	s_waitcnt vmcnt(8)
	v_mfma_f32_32x32x16_bf16 v[64:79], v[146:149], v[98:101], 0
	s_add_i32 s26, s27, 1
	s_cmp_ge_i32 s26, s25
	v_mfma_f32_32x32x16_bf16 v[64:79], v[150:153], v[102:105], v[64:79]
	v_mfma_f32_32x32x16_bf16 v[64:79], v[154:157], v[106:109], v[64:79]
	v_mfma_f32_32x32x16_bf16 v[64:79], v[158:161], v[110:113], v[64:79]
	v_mfma_f32_32x32x16_bf16 v[64:79], v[142:145], v[114:117], v[64:79]
	v_mfma_f32_32x32x16_bf16 v[64:79], v[138:141], v[118:121], v[64:79]
	v_mfma_f32_32x32x16_bf16 v[64:79], v[134:137], v[122:125], v[64:79]
	v_mfma_f32_32x32x16_bf16 v[64:79], v[130:133], v[126:129], v[64:79]
	s_cbranch_scc1 .LBB0_162
	s_sub_i32 s12, s26, s100
	s_cmp_lt_u32 s12, s15
	s_cbranch_scc1 .Latt_lat_nxt
	s_add_i32 s12, s23, 32
	s_cmp_lt_i32 s26, s100
	s_cbranch_scc0 .LBB0_161
	s_lshl_b32 s13, s15, 5
	s_add_i32 s12, s12, s13
	s_branch .LBB0_161
.Latt_lat_nxt:
	s_lshl_b32 s12, s26, 6
	s_add_i32 s12, s12, s24
